# prep0_k per-head rmsnorm wave reductions batched too (7 independent ds_bpermute chains interleaved)
# speedup vs baseline: 1.0120x; 1.0074x over previous
; DEVI bf16_t f2bf(float f) { return (bf16_t)(pk2(f, 0.f) & 0xffffu); }
; DEVI void prep0_k(int sw, const P& p, int item) {
;     ...
; #pragma unroll
;   for (int h = 0; h < 8; ++h) {
;     float ss = wave_sum(a[h] * a[h] + b[h] * b[h] + c0 * c0);
;     float rs = rsqrtf(ss * (1.f / 192.f) + EPS);
;     float x = a[h] * rs * g0, y = b[h] * rs * g1, z = c0 * rs * g2;
;     if (pp >= CTX) z = rope64(z, lane, pp - CTX);
;     k[h * 192 + lane] = f2bf(x); k[h * 192 + 64 + lane] = f2bf(y); k[h * 192 + 128 + lane] = f2bf(z);
.LBB0_453:
	s_mul_hi_u32 s3, s37, 0xc80
	s_mulk_i32 s37, 0xc80
	s_add_u32 s2, s17, s37
	s_addc_u32 s3, s18, s3
	v_mul_f32_e32 v1, v32, v1
	v_mul_f32_e32 v1, v8, v1
	v_mul_f32_e32 v31, v32, v31
	v_mul_f32_e32 v31, v9, v31
	v_cvt_pk_bf16_f32 v1, v1, s0
	v_lshl_add_u64 v[4:5], v[4:5], 1, s[2:3]
	global_store_short v[4:5], v1, off
	v_cvt_pk_bf16_f32 v1, v31, s0
	global_store_short v[4:5], v1, off offset:128
	v_cvt_pk_bf16_f32 v1, v3, s0
	global_store_short v[4:5], v1, off offset:256
	s_movk_i32 s52, 0x400
	s_movk_i32 s53, 0x440
	v_lshlrev_b32_e32 v6, 16, v6
	v_lshlrev_b32_e32 v7, 16, v7
	v_lshlrev_b32_e32 v29, 16, v29
	v_lshlrev_b32_e32 v30, 16, v30
	v_lshlrev_b32_e32 v27, 16, v27
	v_lshlrev_b32_e32 v28, 16, v28
	v_lshlrev_b32_e32 v25, 16, v25
	v_lshlrev_b32_e32 v26, 16, v26
	v_lshlrev_b32_e32 v23, 16, v23
	v_lshlrev_b32_e32 v24, 16, v24
	v_lshlrev_b32_e32 v21, 16, v21
	v_lshlrev_b32_e32 v22, 16, v22
	v_lshlrev_b32_e32 v19, 16, v19
	v_lshlrev_b32_e32 v20, 16, v20
	v_mul_f32_e32 v220, v6, v6
	v_mul_f32_e32 v221, v7, v7
	v_add_f32_e32 v220, v220, v221
	v_add_f32_e32 v220, v2, v220
	v_mul_f32_e32 v224, v29, v29
	v_mul_f32_e32 v225, v30, v30
	v_add_f32_e32 v224, v224, v225
	v_add_f32_e32 v224, v2, v224
	v_mul_f32_e32 v228, v27, v27
	v_mul_f32_e32 v229, v28, v28
	v_add_f32_e32 v228, v228, v229
	v_add_f32_e32 v228, v2, v228
	v_mul_f32_e32 v232, v25, v25
	v_mul_f32_e32 v233, v26, v26
	v_add_f32_e32 v232, v232, v233
	v_add_f32_e32 v232, v2, v232
	v_mul_f32_e32 v236, v23, v23
	v_mul_f32_e32 v237, v24, v24
	v_add_f32_e32 v236, v236, v237
	v_add_f32_e32 v236, v2, v236
	v_mul_f32_e32 v240, v21, v21
	v_mul_f32_e32 v241, v22, v22
	v_add_f32_e32 v240, v240, v241
	v_add_f32_e32 v240, v2, v240
	v_mul_f32_e32 v244, v19, v19
	v_mul_f32_e32 v245, v20, v20
	v_add_f32_e32 v244, v244, v245
	v_add_f32_e32 v244, v2, v244
	ds_bpermute_b32 v221, v15, v220
	ds_bpermute_b32 v225, v15, v224
	ds_bpermute_b32 v229, v15, v228
	ds_bpermute_b32 v233, v15, v232
	ds_bpermute_b32 v237, v15, v236
	ds_bpermute_b32 v241, v15, v240
	ds_bpermute_b32 v245, v15, v244
	s_waitcnt lgkmcnt(0)
	v_add_f32_e32 v220, v220, v221
	v_add_f32_e32 v224, v224, v225
	v_add_f32_e32 v228, v228, v229
	v_add_f32_e32 v232, v232, v233
	v_add_f32_e32 v236, v236, v237
	v_add_f32_e32 v240, v240, v241
	v_add_f32_e32 v244, v244, v245
	ds_bpermute_b32 v221, v10, v220
	ds_bpermute_b32 v225, v10, v224
	ds_bpermute_b32 v229, v10, v228
	ds_bpermute_b32 v233, v10, v232
	ds_bpermute_b32 v237, v10, v236
	ds_bpermute_b32 v241, v10, v240
	ds_bpermute_b32 v245, v10, v244
	s_waitcnt lgkmcnt(0)
	v_add_f32_e32 v220, v220, v221
	v_add_f32_e32 v224, v224, v225
	v_add_f32_e32 v228, v228, v229
	v_add_f32_e32 v232, v232, v233
	v_add_f32_e32 v236, v236, v237
	v_add_f32_e32 v240, v240, v241
	v_add_f32_e32 v244, v244, v245
	ds_bpermute_b32 v221, v16, v220
	ds_bpermute_b32 v225, v16, v224
	ds_bpermute_b32 v229, v16, v228
	ds_bpermute_b32 v233, v16, v232
	ds_bpermute_b32 v237, v16, v236
	ds_bpermute_b32 v241, v16, v240
	ds_bpermute_b32 v245, v16, v244
	s_waitcnt lgkmcnt(0)
	v_add_f32_e32 v220, v220, v221
	v_add_f32_e32 v224, v224, v225
	v_add_f32_e32 v228, v228, v229
	v_add_f32_e32 v232, v232, v233
	v_add_f32_e32 v236, v236, v237
	v_add_f32_e32 v240, v240, v241
	v_add_f32_e32 v244, v244, v245
	ds_bpermute_b32 v221, v17, v220
	ds_bpermute_b32 v225, v17, v224
	ds_bpermute_b32 v229, v17, v228
	ds_bpermute_b32 v233, v17, v232
	ds_bpermute_b32 v237, v17, v236
	ds_bpermute_b32 v241, v17, v240
	ds_bpermute_b32 v245, v17, v244
	s_waitcnt lgkmcnt(0)
	v_add_f32_e32 v220, v220, v221
	v_add_f32_e32 v224, v224, v225
	v_add_f32_e32 v228, v228, v229
	v_add_f32_e32 v232, v232, v233
	v_add_f32_e32 v236, v236, v237
	v_add_f32_e32 v240, v240, v241
	v_add_f32_e32 v244, v244, v245
	ds_bpermute_b32 v221, v18, v220
	ds_bpermute_b32 v225, v18, v224
	ds_bpermute_b32 v229, v18, v228
	ds_bpermute_b32 v233, v18, v232
	ds_bpermute_b32 v237, v18, v236
	ds_bpermute_b32 v241, v18, v240
	ds_bpermute_b32 v245, v18, v244
	s_waitcnt lgkmcnt(0)
	v_add_f32_e32 v220, v220, v221
	v_add_f32_e32 v224, v224, v225
	v_add_f32_e32 v228, v228, v229
	v_add_f32_e32 v232, v232, v233
	v_add_f32_e32 v236, v236, v237
	v_add_f32_e32 v240, v240, v241
	v_add_f32_e32 v244, v244, v245
	ds_bpermute_b32 v221, v14, v220
	ds_bpermute_b32 v225, v14, v224
	ds_bpermute_b32 v229, v14, v228
	ds_bpermute_b32 v233, v14, v232
	ds_bpermute_b32 v237, v14, v236
	ds_bpermute_b32 v241, v14, v240
	ds_bpermute_b32 v245, v14, v244
	s_waitcnt lgkmcnt(0)
; DEVI bf16_t f2bf(float f) { return (bf16_t)(pk2(f, 0.f) & 0xffffu); }
; DEVI float rope64(float val, int lane, int t) {
;   int i = lane & 15, hf = (lane >> 4) & 1, axis = lane >> 5;
;   float pos = (float)(axis ? (t & 63) : (t >> 6));
;   float invf = exp2f(-(float)(2 * i) * (13.287712379549449f / 32.f));
;   float ang = pos * invf;
;   float cs = __cosf(ang), sn = __sinf(ang);
;   float partner = __shfl_xor(val, 16);
;   return hf ? (val * cs + partner * sn) : (val * cs - partner * sn);
; DEVI void prep0_k(int sw, const P& p, int item) {
;     ...
;   for (int h = 0; h < 8; ++h) {
;     float ss = wave_sum(a[h] * a[h] + b[h] * b[h] + c0 * c0);
;     float rs = rsqrtf(ss * (1.f / 192.f) + EPS);
;     float x = a[h] * rs * g0, y = b[h] * rs * g1, z = c0 * rs * g2;
;     if (pp >= CTX) z = rope64(z, lane, pp - CTX);
;     k[h * 192 + lane] = f2bf(x); k[h * 192 + 64 + lane] = f2bf(y); k[h * 192 + 128 + lane] = f2bf(z);
;   }
	v_add_f32_e32 v220, v220, v221
	v_add_f32_e32 v224, v224, v225
	v_add_f32_e32 v228, v228, v229
	v_add_f32_e32 v232, v232, v233
	v_add_f32_e32 v236, v236, v237
	v_add_f32_e32 v240, v240, v241
	v_add_f32_e32 v244, v244, v245
	v_fmamk_f32 v220, v220, 0x3baaaaab, v48
	v_fmamk_f32 v224, v224, 0x3baaaaab, v48
	v_fmamk_f32 v228, v228, 0x3baaaaab, v48
	v_fmamk_f32 v232, v232, 0x3baaaaab, v48
	v_fmamk_f32 v236, v236, 0x3baaaaab, v48
	v_fmamk_f32 v240, v240, 0x3baaaaab, v48
	v_fmamk_f32 v244, v244, 0x3baaaaab, v48
	v_cmp_gt_f32_e32 vcc, s95, v220
	v_mul_f32_e32 v221, 0x4b800000, v220
	s_nop 0
	v_cndmask_b32_e32 v220, v220, v221, vcc
	v_rsq_f32_e32 v220, v220
	s_nop 0
	v_mul_f32_e32 v221, 0x45800000, v220
	v_cndmask_b32_e32 v222, v220, v221, vcc
	v_cmp_gt_f32_e32 vcc, s95, v224
	v_mul_f32_e32 v225, 0x4b800000, v224
	s_nop 0
	v_cndmask_b32_e32 v224, v224, v225, vcc
	v_rsq_f32_e32 v224, v224
	s_nop 0
	v_mul_f32_e32 v225, 0x45800000, v224
	v_cndmask_b32_e32 v226, v224, v225, vcc
	v_cmp_gt_f32_e32 vcc, s95, v228
	v_mul_f32_e32 v229, 0x4b800000, v228
	s_nop 0
	v_cndmask_b32_e32 v228, v228, v229, vcc
	v_rsq_f32_e32 v228, v228
	s_nop 0
	v_mul_f32_e32 v229, 0x45800000, v228
	v_cndmask_b32_e32 v230, v228, v229, vcc
	v_cmp_gt_f32_e32 vcc, s95, v232
	v_mul_f32_e32 v233, 0x4b800000, v232
	s_nop 0
	v_cndmask_b32_e32 v232, v232, v233, vcc
	v_rsq_f32_e32 v232, v232
	s_nop 0
	v_mul_f32_e32 v233, 0x45800000, v232
	v_cndmask_b32_e32 v234, v232, v233, vcc
	v_cmp_gt_f32_e32 vcc, s95, v236
	v_mul_f32_e32 v237, 0x4b800000, v236
	s_nop 0
	v_cndmask_b32_e32 v236, v236, v237, vcc
	v_rsq_f32_e32 v236, v236
	s_nop 0
	v_mul_f32_e32 v237, 0x45800000, v236
	v_cndmask_b32_e32 v238, v236, v237, vcc
	v_cmp_gt_f32_e32 vcc, s95, v240
	v_mul_f32_e32 v241, 0x4b800000, v240
	s_nop 0
	v_cndmask_b32_e32 v240, v240, v241, vcc
	v_rsq_f32_e32 v240, v240
	s_nop 0
	v_mul_f32_e32 v241, 0x45800000, v240
	v_cndmask_b32_e32 v242, v240, v241, vcc
	v_cmp_gt_f32_e32 vcc, s95, v244
	v_mul_f32_e32 v245, 0x4b800000, v244
	s_nop 0
	v_cndmask_b32_e32 v244, v244, v245, vcc
	v_rsq_f32_e32 v244, v244
	s_nop 0
	v_mul_f32_e32 v245, 0x45800000, v244
	v_cndmask_b32_e32 v246, v244, v245, vcc
	v_mul_f32_e32 v223, v222, v0
	v_mul_f32_e32 v223, v11, v223
	v_mul_f32_e32 v227, v226, v0
	v_mul_f32_e32 v227, v11, v227
	v_mul_f32_e32 v231, v230, v0
	v_mul_f32_e32 v231, v11, v231
	v_mul_f32_e32 v235, v234, v0
	v_mul_f32_e32 v235, v11, v235
	v_mul_f32_e32 v239, v238, v0
	v_mul_f32_e32 v239, v11, v239
	v_mul_f32_e32 v243, v242, v0
	v_mul_f32_e32 v243, v11, v243
	v_mul_f32_e32 v247, v246, v0
	v_mul_f32_e32 v247, v11, v247
	s_andn2_b64 vcc, exec, s[4:5]
	s_cbranch_vccnz .Lmy_k0_norope
	ds_bpermute_b32 v221, v10, v223
	ds_bpermute_b32 v225, v10, v227
	ds_bpermute_b32 v229, v10, v231
	ds_bpermute_b32 v233, v10, v235
	ds_bpermute_b32 v237, v10, v239
	ds_bpermute_b32 v241, v10, v243
	ds_bpermute_b32 v245, v10, v247
	s_waitcnt lgkmcnt(0)
	v_mul_f32_e32 v221, v13, v221
	v_cndmask_b32_e64 v221, v221, -v221, s[0:1]
	v_fmac_f32_e32 v221, v12, v223
	v_mov_b32_e32 v223, v221
	v_mul_f32_e32 v225, v13, v225
	v_cndmask_b32_e64 v225, v225, -v225, s[0:1]
	v_fmac_f32_e32 v225, v12, v227
	v_mov_b32_e32 v227, v225
	v_mul_f32_e32 v229, v13, v229
	v_cndmask_b32_e64 v229, v229, -v229, s[0:1]
	v_fmac_f32_e32 v229, v12, v231
	v_mov_b32_e32 v231, v229
	v_mul_f32_e32 v233, v13, v233
	v_cndmask_b32_e64 v233, v233, -v233, s[0:1]
	v_fmac_f32_e32 v233, v12, v235
	v_mov_b32_e32 v235, v233
	v_mul_f32_e32 v237, v13, v237
	v_cndmask_b32_e64 v237, v237, -v237, s[0:1]
	v_fmac_f32_e32 v237, v12, v239
	v_mov_b32_e32 v239, v237
	v_mul_f32_e32 v241, v13, v241
	v_cndmask_b32_e64 v241, v241, -v241, s[0:1]
	v_fmac_f32_e32 v241, v12, v243
	v_mov_b32_e32 v243, v241
	v_mul_f32_e32 v245, v13, v245
	v_cndmask_b32_e64 v245, v245, -v245, s[0:1]
	v_fmac_f32_e32 v245, v12, v247
	v_mov_b32_e32 v247, v245
.Lmy_k0_norope:
	v_mul_f32_e32 v6, v222, v6
	v_mul_f32_e32 v6, v8, v6
	v_cvt_pk_bf16_f32 v6, v6, s0
	global_store_short v[4:5], v6, off offset:384
	v_mul_f32_e32 v7, v222, v7
	v_mul_f32_e32 v7, v9, v7
	v_cvt_pk_bf16_f32 v7, v7, s0
	global_store_short v[4:5], v7, off offset:512
	v_cvt_pk_bf16_f32 v223, v223, s0
	global_store_short v[4:5], v223, off offset:640
	v_mul_f32_e32 v29, v226, v29
	v_mul_f32_e32 v29, v8, v29
	v_cvt_pk_bf16_f32 v29, v29, s0
	global_store_short v[4:5], v29, off offset:768
	v_mul_f32_e32 v30, v226, v30
	v_mul_f32_e32 v30, v9, v30
	v_cvt_pk_bf16_f32 v30, v30, s0
	global_store_short v[4:5], v30, off offset:896
	v_cvt_pk_bf16_f32 v227, v227, s0
	global_store_short v[4:5], v227, off offset:1024
	v_mul_f32_e32 v27, v230, v27
	v_mul_f32_e32 v27, v8, v27
	v_cvt_pk_bf16_f32 v27, v27, s0
	global_store_short v[4:5], v27, off offset:1152
	v_mul_f32_e32 v28, v230, v28
	v_mul_f32_e32 v28, v9, v28
	v_cvt_pk_bf16_f32 v28, v28, s0
	global_store_short v[4:5], v28, off offset:1280
	v_cvt_pk_bf16_f32 v231, v231, s0
	global_store_short v[4:5], v231, off offset:1408
	v_mul_f32_e32 v25, v234, v25
	v_mul_f32_e32 v25, v8, v25
	v_cvt_pk_bf16_f32 v25, v25, s0
	global_store_short v[4:5], v25, off offset:1536
	v_mul_f32_e32 v26, v234, v26
	v_mul_f32_e32 v26, v9, v26
	v_cvt_pk_bf16_f32 v26, v26, s0
	global_store_short v[4:5], v26, off offset:1664
	v_cvt_pk_bf16_f32 v235, v235, s0
	global_store_short v[4:5], v235, off offset:1792
	v_mul_f32_e32 v23, v238, v23
	v_mul_f32_e32 v23, v8, v23
	v_cvt_pk_bf16_f32 v23, v23, s0
	global_store_short v[4:5], v23, off offset:1920
	v_mul_f32_e32 v24, v238, v24
	v_mul_f32_e32 v24, v9, v24
	v_cvt_pk_bf16_f32 v24, v24, s0
	global_store_short v[4:5], v24, off offset:2048
	v_cvt_pk_bf16_f32 v239, v239, s0
	global_store_short v[4:5], v239, off offset:2176
	v_mul_f32_e32 v21, v242, v21
	v_mul_f32_e32 v21, v8, v21
	v_cvt_pk_bf16_f32 v21, v21, s0
	global_store_short v[4:5], v21, off offset:2304
	v_mul_f32_e32 v22, v242, v22
	v_mul_f32_e32 v22, v9, v22
	v_cvt_pk_bf16_f32 v22, v22, s0
	global_store_short v[4:5], v22, off offset:2432
	v_cvt_pk_bf16_f32 v243, v243, s0
	global_store_short v[4:5], v243, off offset:2560
	v_mul_f32_e32 v19, v246, v19
	v_mul_f32_e32 v19, v8, v19
	v_cvt_pk_bf16_f32 v19, v19, s0
	global_store_short v[4:5], v19, off offset:2688
	v_mul_f32_e32 v20, v246, v20
	v_mul_f32_e32 v20, v9, v20
	v_cvt_pk_bf16_f32 v20, v20, s0
	global_store_short v[4:5], v20, off offset:2816
	v_cvt_pk_bf16_f32 v247, v247, s0
	global_store_short v[4:5], v247, off offset:2944
	s_not_b64 s[2:3], s[4:5]
	s_mov_b64 s[38:39], 0
